# half of the workgroups (bit 3 of bid) run the mLSTM chunk phase before the U GEMM, then re-run only its register preamble; overlaps memory-bound and MFMA-bound work
# speedup vs baseline: 1.0023x; 1.0023x over previous
.LBB0_698:
	s_or_b64 exec, exec, s[2:3]
	v_readlane_b32 s2, v253, 21
	s_add_u32 s68, s88, 0x19f00000
	s_waitcnt lgkmcnt(0)
	v_mov_b32_e32 v0, v246
	v_readlane_b32 s3, v253, 22
	s_barrier
	s_addc_u32 s69, s89, 0
	s_bfe_u32 s100, s82, 0x10003
	s_cmp_eq_u32 s100, 0
	s_cbranch_scc1 .Lum_go
	s_branch .LBB0_720
.Lum_reenter:
	v_readlane_b32 s2, v253, 21
	v_readlane_b32 s3, v253, 22
	v_mov_b32_e32 v0, v246
	s_add_u32 s68, s88, 0x19f00000
	s_addc_u32 s69, s89, 0
.Lum_go:
	s_andn2_b64 vcc, exec, s[2:3]
	v_readfirstlane_b32 s2, v0
	s_cbranch_vccnz .LBB0_720
	v_lshlrev_b32_e32 v1, 4, v0
	v_add_u32_e32 v2, 0x2000, v1
	v_ashrrev_i32_e32 v3, 31, v2
	v_lshrrev_b32_e32 v3, 22, v3
	v_add_u32_e32 v3, v2, v3
	v_ashrrev_i32_e32 v3, 10, v3
	v_mul_i32_i24_e32 v4, 0x400, v3
	v_sub_u32_e32 v2, v2, v4
	v_lshrrev_b32_e32 v4, 4, v2
	v_bitop3_b32 v2, v4, v2, 32 bitop3:0x6c
	v_ashrrev_i32_e32 v4, 31, v2
	v_lshrrev_b32_e32 v4, 26, v4
	v_add_u32_e32 v4, v2, v4
	v_lshlrev_b32_e32 v6, 3, v3
	v_ashrrev_i32_e32 v5, 6, v4
	v_and_b32_e32 v6, -16, v6
	v_add_u32_e32 v6, v5, v6
	v_and_b32_e32 v5, 3, v5
	s_mov_b32 s8, 0x1ffffe0
	v_lshrrev_b32_e32 v7, 2, v6
	v_lshlrev_b32_e32 v8, 1, v6
	v_and_b32_e32 v4, 0xc0, v4
	v_and_or_b32 v5, v6, s8, v5
	v_and_b32_e32 v7, 4, v7
	v_and_b32_e32 v8, 24, v8
	v_lshlrev_b32_e32 v3, 5, v3
	v_sub_u32_e32 v2, v2, v4
	v_or3_b32 v5, v5, v7, v8
	s_movk_i32 s7, 0x180
	v_and_b32_e32 v3, 32, v3
	v_ashrrev_i16_sdwa v2, v196, sext(v2) dst_sel:DWORD dst_unused:UNUSED_PAD src0_sel:DWORD src1_sel:BYTE_0
	s_movk_i32 s9, 0x1b00
	v_mul_lo_u32 v5, v5, s7
	v_add_u32_sdwa v2, v3, sext(v2) dst_sel:DWORD dst_unused:UNUSED_PAD src0_sel:DWORD src1_sel:WORD_0
	v_mul_lo_u32 v3, v6, s9
	v_add_lshl_u32 v130, v5, v2, 1
	v_add_lshl_u32 v132, v2, v3, 1
	v_bfe_i32 v2, v0, 27, 1
	v_lshrrev_b32_e32 v2, 22, v2
	v_add_u32_e32 v2, v1, v2
	v_and_b32_e32 v2, 0xfffffc00, v2
	v_sub_u32_e32 v1, v1, v2
	v_lshrrev_b32_e32 v2, 4, v1
	v_ashrrev_i32_e32 v4, 31, v0
	v_bitop3_b32 v1, v2, v1, 32 bitop3:0x6c
	v_lshrrev_b32_e32 v4, 26, v4
	v_ashrrev_i32_e32 v2, 31, v1
	v_add_u32_e32 v4, v0, v4
	v_lshrrev_b32_e32 v2, 26, v2
	v_ashrrev_i32_e32 v4, 6, v4
	v_add_u32_e32 v2, v1, v2
	v_lshlrev_b32_e32 v5, 3, v4
	v_ashrrev_i32_e32 v3, 6, v2
	v_and_b32_e32 v5, -16, v5
	s_add_u32 s34, s88, 0x7601800
	v_add_u32_e32 v5, v3, v5
	s_addc_u32 s36, s89, 0
	v_readlane_b32 s3, v255, 27
	v_and_b32_e32 v3, 3, v3
	v_lshrrev_b32_e32 v6, 2, v5
	v_lshlrev_b32_e32 v7, 1, v5
	s_add_u32 s37, s3, 0x1080000
	v_readlane_b32 s3, v255, 28
	v_and_or_b32 v3, v5, s8, v3
	v_and_b32_e32 v6, 4, v6
	v_and_b32_e32 v7, 24, v7
	s_addc_u32 s39, s3, 0
	s_ashr_i32 s3, s2, 6
	v_or3_b32 v3, v3, v6, v7
	v_readlane_b32 s8, v254, 9
	s_ashr_i32 s6, s2, 8
	s_lshl_b32 s40, s3, 10
	v_mul_lo_u32 v3, v3, s7
	s_mul_i32 s7, s8, 0x360000
	v_and_b32_e32 v2, 0xc0, v2
	s_add_u32 s7, s34, s7
	s_mul_hi_i32 s8, s8, 0x360000
	v_lshlrev_b32_e32 v4, 5, v4
	v_sub_u32_e32 v1, v1, v2
	s_addc_u32 s10, s36, s8
	v_readlane_b32 s8, v254, 13
	v_and_b32_e32 v4, 32, v4
	v_ashrrev_i16_sdwa v1, v196, sext(v1) dst_sel:DWORD dst_unused:UNUSED_PAD src0_sel:DWORD src1_sel:BYTE_0
	s_add_u32 s18, s37, s8
	v_readlane_b32 s8, v254, 12
	v_add_u32_sdwa v1, v4, sext(v1) dst_sel:DWORD dst_unused:UNUSED_PAD src0_sel:DWORD src1_sel:WORD_0
	s_addc_u32 s19, s39, s8
	s_add_i32 s41, s40, 0
	v_add_lshl_u32 v112, v3, v1, 1
	s_add_i32 m0, s41, 0x10000
	v_mul_lo_u32 v2, v5, s9
	global_load_lds_dwordx4 v112, s[18:19]
	s_add_i32 m0, s41, 0x12000
	s_add_u32 s8, s18, 0x18000
	global_load_lds_dwordx4 v130, s[18:19]
	s_addc_u32 s9, s19, 0
	s_add_i32 m0, s41, 0x14000
	v_add_lshl_u32 v134, v1, v2, 1
	global_load_lds_dwordx4 v112, s[8:9]
	s_add_i32 m0, s41, 0x16000
	s_nop 0
	global_load_lds_dwordx4 v130, s[8:9]
	v_readlane_b32 s8, v254, 11
	s_add_u32 s16, s7, s8
	s_addc_u32 s17, s10, 0
	s_add_i32 s42, s41, 0x2000
	s_mov_b32 m0, s41
	s_add_u32 s8, s16, 0x1b0000
	global_load_lds_dwordx4 v134, s[16:17]
	s_mov_b32 m0, s42
	s_addc_u32 s9, s17, 0
	s_add_i32 s43, s41, 0x4000
	global_load_lds_dwordx4 v132, s[16:17]
	s_mov_b32 m0, s43
	s_add_i32 s44, s41, 0x6000
	global_load_lds_dwordx4 v134, s[8:9]
	s_mov_b32 m0, s44
	s_cmp_eq_u32 s6, 1
	global_load_lds_dwordx4 v132, s[8:9]
	s_cselect_b64 s[10:11], -1, 0
	s_cmp_lg_u32 s6, 1
	s_cbranch_scc1 .LBB0_701
	s_barrier

.LBB0_733:
	v_and_b32_e32 v1, 31, v28
	v_ashrrev_i32_e32 v5, 7, v28
	v_lshl_or_b32 v6, v5, 5, v1
	v_mul_lo_u32 v6, v6, s20
	v_add_u32_e32 v33, 0xffffff00, v28
	v_and_b32_e32 v2, 63, v28
	v_lshl_add_u32 v32, v30, 2, 0
	v_add_u32_e32 v11, 0, v6
	v_lshrrev_b32_e32 v6, 1, v28
	s_movk_i32 s2, 0x8c
	v_lshlrev_b32_e32 v8, 2, v2
	v_ashrrev_i32_e32 v31, 31, v30
	v_and_or_b32 v1, v6, 32, v1
	v_mad_u64_u32 v[6:7], s[2:3], v30, s2, v[32:33]
	v_add_u32_e32 v42, 0, v8
	v_xor_b32_e32 v44, 4, v8
	v_xor_b32_e32 v45, 8, v8
	v_xor_b32_e32 v46, 16, v8
	v_lshl_add_u64 v[8:9], v[30:31], 2, s[88:89]
	s_mov_b64 s[2:3], 0x1fd00000
	v_lshl_add_u64 v[34:35], v[8:9], 0, s[2:3]
	v_lshlrev_b32_e32 v8, 2, v28
	v_add_u32_e32 v9, 0xfc, v8
	v_and_b32_e32 v31, 0xfc, v9
	v_add_u32_e32 v9, 0xf8, v8
	v_bfe_u32 v3, v28, 5, 1
	v_and_b32_e32 v47, 0xfc, v9
	v_add_u32_e32 v9, 0xf0, v8
	v_lshlrev_b32_e32 v12, 4, v3
	v_lshlrev_b32_e32 v5, 11, v5
	v_lshlrev_b32_e32 v3, 8, v3
	v_and_b32_e32 v48, 0xfc, v9
	v_add_u32_e32 v9, 0xe0, v8
	s_add_u32 s14, s88, 0x1fe30000
	v_lshlrev_b32_e32 v4, 3, v0
	v_lshlrev_b32_e32 v7, 4, v0
	v_cmp_eq_u32_e64 s[48:49], 0, v0
	v_and_b32_e32 v49, 0xfc, v9
	v_add_u32_e32 v9, 0xc0, v8
	v_xor_b32_e32 v51, 0x80, v8
	v_mad_u32_u24 v8, v0, s91, 0
	v_or3_b32 v0, v3, v5, v1
	v_readlane_b32 s2, v255, 23
	s_addc_u32 s15, s89, 0
	v_mad_u32_u24 v13, v1, s20, 0
	v_ashrrev_i32_e32 v1, 31, v0
	v_readlane_b32 s3, v255, 24
	s_add_u32 s16, s88, 0x1fe20000
	s_addc_u32 s17, s89, 0
	v_lshl_add_u64 v[36:37], v[0:1], 1, s[2:3]
	v_readlane_b32 s2, v253, 44
	v_lshlrev_b32_e32 v10, 1, v30
	s_lshl_b32 s2, s2, 6
	v_cmp_gt_u32_e64 s[44:45], 64, v28
	v_mov_b32_e32 v29, v113
	v_cmp_eq_u32_e64 s[46:47], 0, v2
	v_add_u32_e32 v43, 0xffffff00, v30
	v_cmp_gt_u32_e64 s[50:51], 2, v2
	v_cmp_gt_u32_e64 s[52:53], 4, v2
	v_cmp_gt_u32_e64 s[54:55], 8, v2
	v_and_b32_e32 v50, 0xfc, v9
	v_cmp_gt_u32_e64 s[56:57], 16, v2
	v_cmp_gt_u32_e64 s[58:59], 32, v2
	s_sub_i32 s18, 0, s2
	v_sub_u32_e32 v52, 0, v30
	s_lshl_b32 s19, s86, 6
	v_sub_u32_e32 v53, 0, v28
	v_lshlrev_b32_e32 v112, 2, v2
	v_add_u32_e32 v54, v8, v10
	v_lshlrev_b32_e32 v40, 1, v4
	v_add_u32_e32 v55, v11, v12
	v_add_u32_e32 v56, v13, v12
	v_add_u32_e32 v57, v6, v7
	v_lshrrev_b32_e32 v68, 3, v28
	v_and_b32_e32 v69, 7, v28
	v_lshrrev_b32_e32 v70, 3, v68
	v_xor_b32_e32 v70, v70, v69
	v_and_b32_e32 v71, 7, v68
	v_lshlrev_b32_e32 v71, 1, v71
	v_lshl_add_u32 v71, v70, 4, v71
	s_movk_i32 s2, 0x480
	v_mad_u32_u24 v54, v69, s2, v71
	v_mul_u32_u24_e32 v71, 0x90, v68
	v_lshl_add_u32 v57, v70, 4, v71
	v_and_b32_e32 v72, 31, v28
	v_bfe_u32 v73, v28, 5, 1
	v_lshrrev_b32_e32 v74, 7, v28
	v_lshl_or_b32 v75, v74, 5, v72
	v_bfe_u32 v76, v28, 6, 1
	v_lshl_or_b32 v77, v76, 5, v72
	v_bfe_u32 v78, v75, 3, 3
	v_bfe_u32 v79, v77, 3, 3
	v_mul_u32_u24_e32 v75, 0x90, v75
	v_mul_u32_u24_e32 v77, 0x90, v77
	v_or_b32_e32 v70, 0, v73
	v_xor_b32_e32 v71, v70, v78
	v_lshl_add_u32 v80, v71, 4, v75
	v_xor_b32_e32 v71, v70, v79
	v_lshl_add_u32 v84, v71, 4, v77
	v_or_b32_e32 v70, 2, v73
	v_xor_b32_e32 v71, v70, v78
	v_lshl_add_u32 v81, v71, 4, v75
	v_xor_b32_e32 v71, v70, v79
	v_lshl_add_u32 v85, v71, 4, v77
	v_or_b32_e32 v70, 4, v73
	v_xor_b32_e32 v71, v70, v78
	v_lshl_add_u32 v82, v71, 4, v75
	v_xor_b32_e32 v71, v70, v79
	v_lshl_add_u32 v86, v71, 4, v77
	v_or_b32_e32 v70, 6, v73
	v_xor_b32_e32 v71, v70, v78
	v_lshl_add_u32 v83, v71, 4, v75
	v_xor_b32_e32 v71, v70, v79
	v_lshl_add_u32 v87, v71, 4, v77
	s_cmp_eq_u32 s100, 2
	s_cbranch_scc1 .LBB0_768
	s_and_saveexec_b64 s[2:3], s[44:45]
	s_cbranch_execz .Lmla_tab_done
	s_load_dwordx4 s[8:11], s[84:85], 0x48
	v_and_b32_e32 v0, 15, v2
	v_lshlrev_b32_e32 v0, 2, v0
	s_waitcnt lgkmcnt(0)
	global_load_dword v1, v0, s[8:9]
	global_load_dword v3, v0, s[10:11]
	v_add_u32_e32 v0, 0x22340, v0
	s_waitcnt vmcnt(0)
	ds_write_b32 v0, v1
	ds_write_b32 v0, v3 offset:64
	s_waitcnt lgkmcnt(0)

.Lum_exit:
	s_cmp_eq_u32 s100, 1
	s_cbranch_scc0 .LBB0_768
	s_mov_b32 s100, 2
	s_waitcnt vmcnt(0) lgkmcnt(0)
	s_barrier
	s_branch .Lum_reenter
